# full grid barriers: the XCD leader invalidates L2 right after its L2 writeback (overlapping the cross-XCD round, nobody on the XCD fetches data until release); released workgroups invalidate only L1
# speedup vs baseline: 1.0137x; 1.0137x over previous
.LBB0_114:
	s_andn2_saveexec_b64 s[0:1], s[10:11]
	s_cbranch_execz .LBB0_147
	s_mov_b64 s[10:11], exec
	buffer_wbl2 sc1
	s_waitcnt vmcnt(0)
	buffer_inv sc1
	s_waitcnt lgkmcnt(0)
	s_waitcnt vmcnt(0)
	v_mbcnt_lo_u32_b32 v0, s10, 0
	v_mbcnt_hi_u32_b32 v0, s11, v0
	v_cmp_eq_u32_e32 vcc, 0, v0
	s_and_saveexec_b64 s[12:13], vcc
	s_cbranch_execz .LBB0_117
	s_bcnt1_i32_b64 s0, s[10:11]
	v_mov_b32_e32 v2, 0x7000
	v_mov_b32_e32 v3, s0
	global_atomic_add v2, v2, v3, s[6:7] offset:1024 sc0

.LBB0_144:
	s_or_b64 exec, exec, s[10:11]
	s_mov_b64 s[6:7], exec
	v_mbcnt_lo_u32_b32 v0, s6, 0
	v_mbcnt_hi_u32_b32 v0, s7, v0
	v_cmp_eq_u32_e32 vcc, 0, v0
	s_waitcnt vmcnt(0)
	buffer_inv sc0
	s_waitcnt vmcnt(0)
	s_and_saveexec_b64 s[10:11], vcc
	s_cbranch_execz .LBB0_146
	s_bcnt1_i32_b64 s0, s[6:7]
	v_mov_b32_e32 v0, 0x2000
	v_mov_b32_e32 v1, s0
	global_atomic_add v0, v1, s[8:9] offset:1024

.LBB0_203:
	s_andn2_saveexec_b64 s[2:3], s[10:11]
	s_cbranch_execz .LBB0_236
	s_mov_b64 s[10:11], exec
	buffer_wbl2 sc1
	s_waitcnt vmcnt(0)
	buffer_inv sc1
	s_waitcnt lgkmcnt(0)
	s_waitcnt vmcnt(0)
	v_mbcnt_lo_u32_b32 v0, s10, 0
	v_mbcnt_hi_u32_b32 v0, s11, v0
	v_cmp_eq_u32_e32 vcc, 0, v0
	s_and_saveexec_b64 s[12:13], vcc
	s_cbranch_execz .LBB0_206
	s_bcnt1_i32_b64 s2, s[10:11]
	v_mov_b32_e32 v3, s2
	global_atomic_add v3, v254, v3, s[6:7] offset:1024 sc0

.LBB0_233:
	s_or_b64 exec, exec, s[10:11]
	s_mov_b64 s[6:7], exec
	v_mbcnt_lo_u32_b32 v0, s6, 0
	v_mbcnt_hi_u32_b32 v0, s7, v0
	v_cmp_eq_u32_e32 vcc, 0, v0
	s_waitcnt vmcnt(0)
	buffer_inv sc0
	s_waitcnt vmcnt(0)
	s_and_saveexec_b64 s[10:11], vcc
	s_cbranch_execz .LBB0_235
	s_bcnt1_i32_b64 s2, s[6:7]
	v_mov_b32_e32 v0, s2
	global_atomic_add v231, v0, s[8:9] offset:1024

.LBB0_559:
	s_andn2_saveexec_b64 s[2:3], s[10:11]
	s_cbranch_execz .LBB0_592
	s_mov_b64 s[10:11], exec
	v_readlane_b32 s2, v255, 40
	s_nop 0
	s_cmp_lg_u32 s2, 0
	s_cbranch_scc1 .Lglu_nowb
	buffer_wbl2 sc1
	s_waitcnt vmcnt(0)
	buffer_inv sc1

.LBB0_726:
	s_andn2_saveexec_b64 s[2:3], s[10:11]
	s_cbranch_execz .LBB0_759
	s_mov_b64 s[10:11], exec
	v_readlane_b32 s2, v255, 40
	s_nop 0
	s_cmp_lg_u32 s2, 0
	s_cbranch_scc1 .LBB0_756
	buffer_wbl2 sc1
	s_waitcnt vmcnt(0)
	buffer_inv sc1
	s_waitcnt lgkmcnt(0)
	s_waitcnt vmcnt(0)
	v_mbcnt_lo_u32_b32 v0, s10, 0
	v_mbcnt_hi_u32_b32 v0, s11, v0
	v_cmp_eq_u32_e32 vcc, 0, v0
	s_and_saveexec_b64 s[12:13], vcc
	s_cbranch_execz .LBB0_729
	s_bcnt1_i32_b64 s2, s[10:11]
	v_mov_b32_e32 v3, s2
	global_atomic_add v3, v254, v3, s[6:7] offset:1024 sc0

.LBB0_1139:
	s_andn2_saveexec_b64 s[2:3], s[12:13]
	s_cbranch_execz .LBB0_1172
	s_mov_b64 s[12:13], exec
	v_readlane_b32 s2, v255, 40
	s_nop 0
	s_cmp_lg_u32 s2, 0
	s_cbranch_scc1 .LBB0_1169
	buffer_wbl2 sc1
	s_waitcnt vmcnt(0)
	buffer_inv sc1
	s_waitcnt lgkmcnt(0)
	s_waitcnt vmcnt(0)
	v_mbcnt_lo_u32_b32 v0, s12, 0
	v_mbcnt_hi_u32_b32 v0, s13, v0
	v_cmp_eq_u32_e32 vcc, 0, v0
	s_and_saveexec_b64 s[14:15], vcc
	s_cbranch_execz .LBB0_1142
	s_bcnt1_i32_b64 s2, s[12:13]
	v_mov_b32_e32 v3, s2
	global_atomic_add v3, v254, v3, s[6:7] offset:1024 sc0

.LBB0_1169:
	s_or_b64 exec, exec, s[12:13]
	s_mov_b64 s[6:7], exec
	v_mbcnt_lo_u32_b32 v0, s6, 0
	v_mbcnt_hi_u32_b32 v0, s7, v0
	v_cmp_eq_u32_e32 vcc, 0, v0
	s_waitcnt vmcnt(0)
	buffer_inv sc0
	s_waitcnt vmcnt(0)
	s_and_saveexec_b64 s[12:13], vcc
	s_cbranch_execz .LBB0_1171
	s_bcnt1_i32_b64 s2, s[6:7]
	v_mov_b32_e32 v0, s2
	global_atomic_add v231, v0, s[8:9] offset:1024

.LBB0_1344:
	s_mov_b64 s[12:13], exec
	v_readlane_b32 s2, v255, 40
	s_and_b64 vcc, exec, s[10:11]
	s_cselect_b32 s3, 1, 0
	s_and_b32 s2, s2, s3
	s_cmp_lg_u32 s2, 0
	s_cbranch_scc1 .LBB0_1373
	buffer_wbl2 sc1
	s_waitcnt vmcnt(0)
	buffer_inv sc1
	s_waitcnt lgkmcnt(0)
	s_waitcnt vmcnt(0)
	v_mbcnt_lo_u32_b32 v0, s12, 0
	v_mbcnt_hi_u32_b32 v0, s13, v0
	v_cmp_eq_u32_e32 vcc, 0, v0
	s_and_saveexec_b64 s[14:15], vcc
	s_cbranch_execz .LBB0_1346
	s_bcnt1_i32_b64 s2, s[12:13]
	v_mov_b32_e32 v3, s2
	global_atomic_add v3, v254, v3, s[6:7] offset:1024 sc0

.LBB0_1373:
	s_or_b64 exec, exec, s[12:13]
	s_mov_b64 s[6:7], exec
	v_mbcnt_lo_u32_b32 v0, s6, 0
	v_mbcnt_hi_u32_b32 v0, s7, v0
	v_cmp_eq_u32_e32 vcc, 0, v0
	s_waitcnt vmcnt(0)
	buffer_inv sc0
	s_waitcnt vmcnt(0)
	s_and_saveexec_b64 s[12:13], vcc
	s_cbranch_execnz .LBB0_1374
	s_getpc_b64 s[98:99]
